# second layer-0 residual row-phase call (context rows): parameter set-up loop de-serialised as well
# baseline (speedup 1.0000x reference)
; template <bool HAS_Y, bool WRITE_X, bool HAS_XN> ...
;     for (int idx = tid; idx < 5 * DM; idx += NTHR) { const int r = idx >> 10, c = idx & (DM - 1);
;         if (HAS_Y) PRM[idx] = mods_y[((size_t)r * 6 + gate_idx) * DM + c] * ngy[c];
;         if (HAS_XN) { PRM[5 * DM + idx] = ng2[c] * (1.0f + mods_n[((size_t)r * 6 + sc_idx) * DM + c]); PRM[10 * DM + idx] = mods_n[((size_t)r * 6 + sh_idx) * DM + c]; } }
;     __syncthreads();
;     ...
;     RowRegs A, B, C, D;
;     int row = gw;
;     if (row < MROWS) {
;         row_load<HAS_Y>(A, row, ROW_ON(row), lane, xin_lat, xin_ctx, Y); row_load<HAS_Y>(B, row + NGW, ROW_ON(row + NGW), lane, xin_lat, xin_ctx, Y);
; __global__ void __launch_bounds__(mk::NTHR, 2) fwd_kernel(Args args) {
;     ...
;         row_phase<true, true, true>(gw, NGW, lane, tid, (float*)lds, 2, x, ctx, out, CTXS, Y, mods, 2, norm_g + 1 * DM, norm_g + 2 * DM, mods, 3, 4, XN);
.LBB0_753:
	global_load_dword v8, v4, s[4:5]
	global_load_dword v9, v4, s[4:5] offset:2048
	global_load_dword v10, v4, s[8:9]
	global_load_dword v11, v4, s[8:9] offset:2048
	s_add_u32 s10, s94, 0x2000
	s_addc_u32 s11, s95, 0
	s_add_u32 s12, s94, 0x3000
	s_addc_u32 s13, s95, 0
	s_add_u32 s98, s94, 0x4000
	s_addc_u32 s99, s95, 0
	global_load_dword v12, v4, s[10:11]
	global_load_dword v13, v4, s[10:11] offset:2048
	global_load_dword v14, v4, s[12:13]
	global_load_dword v15, v4, s[12:13] offset:2048
	global_load_dword v16, v4, s[98:99]
	global_load_dword v17, v4, s[98:99] offset:2048
	s_add_u32 s10, s94, 0x8000
	s_addc_u32 s11, s95, 0
	s_add_u32 s12, s94, 0x9000
	s_addc_u32 s13, s95, 0
	s_add_u32 s98, s94, 0xa000
	s_addc_u32 s99, s95, 0
	global_load_dword v18, v4, s[10:11]
	global_load_dword v19, v4, s[10:11] offset:2048
	global_load_dword v20, v4, s[12:13]
	global_load_dword v21, v4, s[12:13] offset:2048
	global_load_dword v22, v4, s[98:99]
	global_load_dword v23, v4, s[98:99] offset:2048
	s_add_u32 s10, s94, 0xe000
	s_addc_u32 s11, s95, 0
	s_add_u32 s12, s94, 0xf000
	s_addc_u32 s13, s95, 0
	s_add_u32 s98, s94, 0x10000
	s_addc_u32 s99, s95, 0
	global_load_dword v24, v4, s[10:11]
	global_load_dword v25, v4, s[10:11] offset:2048
	global_load_dword v26, v4, s[12:13]
	global_load_dword v27, v4, s[12:13] offset:2048
	global_load_dword v28, v4, s[98:99]
	global_load_dword v29, v4, s[98:99] offset:2048
	s_add_u32 s10, s94, 0x14000
	s_addc_u32 s11, s95, 0
	s_add_u32 s12, s94, 0x15000
	s_addc_u32 s13, s95, 0
	s_add_u32 s98, s94, 0x16000
	s_addc_u32 s99, s95, 0
	global_load_dword v30, v4, s[10:11]
	global_load_dword v31, v4, s[10:11] offset:2048
	global_load_dword v32, v4, s[12:13]
	global_load_dword v33, v4, s[12:13] offset:2048
	global_load_dword v34, v4, s[98:99]
	global_load_dword v35, v4, s[98:99] offset:2048
	s_add_u32 s10, s94, 0x1a000
	s_addc_u32 s11, s95, 0
	s_add_u32 s12, s94, 0x1b000
	s_addc_u32 s13, s95, 0
	s_add_u32 s98, s94, 0x1c000
	s_addc_u32 s99, s95, 0
	global_load_dword v36, v4, s[10:11]
	global_load_dword v37, v4, s[10:11] offset:2048
	global_load_dword v38, v4, s[12:13]
	global_load_dword v39, v4, s[12:13] offset:2048
	global_load_dword v40, v4, s[98:99]
	global_load_dword v41, v4, s[98:99] offset:2048
	s_waitcnt vmcnt(0)
	v_mul_f32_e32 v12, v12, v8
	v_add_f32_e32 v16, 1.0, v16
	v_mul_f32_e32 v16, v10, v16
	ds_write_b32 v4, v14 offset:40960
	ds_write2st64_b32 v4, v12, v16 offset0:0 offset1:80
	v_mul_f32_e32 v13, v13, v9
	v_add_f32_e32 v17, 1.0, v17
	v_mul_f32_e32 v17, v11, v17
	ds_write_b32 v4, v15 offset:43008
	ds_write2st64_b32 v4, v13, v17 offset0:8 offset1:88
	v_mul_f32_e32 v18, v18, v8
	v_add_f32_e32 v22, 1.0, v22
	v_mul_f32_e32 v22, v10, v22
	ds_write_b32 v4, v20 offset:45056
	ds_write2st64_b32 v4, v18, v22 offset0:16 offset1:96
	v_mul_f32_e32 v19, v19, v9
	v_add_f32_e32 v23, 1.0, v23
	v_mul_f32_e32 v23, v11, v23
	ds_write_b32 v4, v21 offset:47104
	ds_write2st64_b32 v4, v19, v23 offset0:24 offset1:104
	v_mul_f32_e32 v24, v24, v8
	v_add_f32_e32 v28, 1.0, v28
	v_mul_f32_e32 v28, v10, v28
	ds_write_b32 v4, v26 offset:49152
	ds_write2st64_b32 v4, v24, v28 offset0:32 offset1:112
	v_mul_f32_e32 v25, v25, v9
	v_add_f32_e32 v29, 1.0, v29
	v_mul_f32_e32 v29, v11, v29
	ds_write_b32 v4, v27 offset:51200
	ds_write2st64_b32 v4, v25, v29 offset0:40 offset1:120
	v_mul_f32_e32 v30, v30, v8
	v_add_f32_e32 v34, 1.0, v34
	v_mul_f32_e32 v34, v10, v34
	ds_write_b32 v4, v32 offset:53248
	ds_write2st64_b32 v4, v30, v34 offset0:48 offset1:128
	v_mul_f32_e32 v31, v31, v9
	v_add_f32_e32 v35, 1.0, v35
	v_mul_f32_e32 v35, v11, v35
	ds_write_b32 v4, v33 offset:55296
	ds_write2st64_b32 v4, v31, v35 offset0:56 offset1:136
	v_mul_f32_e32 v36, v36, v8
	v_add_f32_e32 v40, 1.0, v40
	v_mul_f32_e32 v40, v10, v40
	ds_write_b32 v4, v38 offset:57344
	ds_write2st64_b32 v4, v36, v40 offset0:64 offset1:144
	v_mul_f32_e32 v37, v37, v9
	v_add_f32_e32 v41, 1.0, v41
	v_mul_f32_e32 v41, v11, v41
	ds_write_b32 v4, v39 offset:59392
	ds_write2st64_b32 v4, v37, v41 offset0:72 offset1:152
	s_cmp_lt_i32 s46, 0x8400
	s_waitcnt lgkmcnt(0)
	s_barrier
	s_cbranch_scc0 .LBB0_825
	s_mul_hi_i32 s4, s46, 0x3e0f83e1
	s_lshr_b32 s5, s4, 31
	s_ashr_i32 s9, s4, 11
	s_add_i32 s9, s9, s5
	s_mul_i32 s4, s9, 0x2100
	s_sub_i32 s4, s46, s4
	s_cmpk_lt_i32 s4, 0x2000
	s_cbranch_scc1 .LBB0_758
	s_mul_i32 s12, s9, 0xffffdf00
	s_add_i32 s12, s12, s46
	s_cmpk_lt_i32 s12, 0x2000
	s_cbranch_scc0 .LBB0_759
	s_lshl_b32 s4, s9, 13
	s_add_i32 s8, s12, s4
	s_mov_b64 s[4:5], s[48:49]
	s_cbranch_execz .LBB0_760
	s_branch .LBB0_761

; __global__ void __launch_bounds__(mk::NTHR, 2) fwd_kernel(Args args) {
;     ...
;     if (IN(13)) {
;         for (int u = vcu; u < 1024; u += G) { const int qb = u & 31, gq = (u >> 5) & 3, kvh = (u >> 7) & 1, b = u >> 8, h = kvh * 4 + gq;
.LBB0_1582:
	s_nop 0
	s_nop 0
	s_nop 0
	s_nop 0
	s_nop 0
	s_nop 0
	s_nop 0
	s_nop 0
	s_nop 0
	s_nop 0
	s_nop 0
	s_nop 0
	s_nop 0
	s_nop 0
	s_nop 0
	s_nop 0
	s_nop 0
	s_nop 0
	s_nop 0
	s_nop 0
	s_nop 0
	s_nop 0
	s_nop 0
	s_nop 0
	s_nop 0
	s_nop 0
	s_nop 0
	s_nop 0
	s_nop 0
	s_nop 0
	s_cmp_lt_i32 s84, 14
	s_cselect_b64 s[4:5], -1, 0
	s_and_b64 s[28:29], s[4:5], s[2:3]
	s_xor_b64 s[2:3], s[28:29], -1
	s_cmpk_gt_i32 s33, 0x3ff
	s_cselect_b64 s[4:5], -1, 0
	s_or_b64 s[2:3], s[2:3], s[4:5]
	s_and_b64 vcc, exec, s[2:3]
	s_cbranch_vccnz .LBB0_1602
	v_readfirstlane_b32 s98, v0
	s_bitcmp1_b32 s98, 8
	s_cbranch_scc0 .Lattn_noprio
	s_setprio 1
